# attention u-loop: dead flag test and redundant branch removed, half-index compare replaces flag toggling (both layers)
# baseline (speedup 1.0000x reference)
.Lhwat0_tail:
.LBB0_881:
	s_bitcmp1_b32 s34, 0
	s_cselect_b32 s28, 0x5800, 0
	v_or_b32_e32 v201, s28, v144
	s_mov_b32 s68, 0
	v_add_u32_e32 v202, v201, v198
	s_and_b64 vcc, exec, s[62:63]
	v_lshl_or_b32 v203, s68, 5, v190
	s_cbranch_vccnz .LBB0_883
.LBB0_882:
	v_mad_u32_u24 v212, v203, s82, v201
	ds_read_b128 v[64:67], v212
	ds_read_b128 v[204:207], v212 offset:32
	ds_read_b128 v[208:211], v212 offset:64
	ds_read_b128 v[246:249], v212 offset:96
	s_waitcnt lgkmcnt(2)
	v_mfma_f32_32x32x16_bf16 v[80:95], v[64:67], v[96:99], 0
	v_mfma_f32_32x32x16_bf16 v[64:79], v[64:67], v[136:139], 0
	v_mfma_f32_32x32x16_bf16 v[80:95], v[204:207], v[100:103], v[80:95]
	v_mfma_f32_32x32x16_bf16 v[64:79], v[204:207], v[120:123], v[64:79]
	ds_read_b128 v[204:207], v212 offset:128
	ds_read_b128 v[250:253], v212 offset:160
	s_waitcnt lgkmcnt(2)
	v_mfma_f32_32x32x16_bf16 v[80:95], v[208:211], v[104:107], v[80:95]
	v_mfma_f32_32x32x16_bf16 v[64:79], v[208:211], v[124:127], v[64:79]
	v_mfma_f32_32x32x16_bf16 v[80:95], v[246:249], v[108:111], v[80:95]
	v_mfma_f32_32x32x16_bf16 v[64:79], v[246:249], v[128:131], v[64:79]
	s_waitcnt lgkmcnt(0)
	v_mfma_f32_32x32x16_bf16 v[80:95], v[204:207], v[112:115], v[80:95]
	v_mfma_f32_32x32x16_bf16 v[64:79], v[204:207], v[132:135], v[64:79]
	v_mfma_f32_32x32x16_bf16 v[80:95], v[250:253], v[116:119], v[80:95]
	v_mfma_f32_32x32x16_bf16 v[64:79], v[250:253], v[140:143], v[64:79]

.LBB0_887:
	v_lshl_add_u32 v203, s68, 6, v202
	v_exp_f32_e32 v209, v80
	v_exp_f32_e32 v211, v81
	v_exp_f32_e32 v213, v82
	v_exp_f32_e32 v215, v83
	ds_read_b128 v[80:83], v203 offset:13312
	ds_read_b128 v[204:207], v203 offset:17920
	v_exp_f32_e32 v217, v84
	v_exp_f32_e32 v219, v85
	v_exp_f32_e32 v221, v86
	v_exp_f32_e32 v223, v87
	v_exp_f32_e32 v208, v64
	v_exp_f32_e32 v210, v65
	v_exp_f32_e32 v212, v66
	v_exp_f32_e32 v214, v67
	v_exp_f32_e32 v216, v68
	v_exp_f32_e32 v218, v69
	v_exp_f32_e32 v220, v70
	v_exp_f32_e32 v222, v71
	v_cvt_pk_bf16_f32 v64, v209, v211
	v_cvt_pk_bf16_f32 v65, v213, v215
	v_cvt_pk_bf16_f32 v66, v217, v219
	v_cvt_pk_bf16_f32 v67, v221, v223
	v_cvt_pk_bf16_f32 v68, v208, v210
	v_cvt_pk_bf16_f32 v69, v212, v214
	v_cvt_pk_bf16_f32 v70, v216, v218
	v_cvt_pk_bf16_f32 v71, v220, v222
	ds_read_b128 v[84:87], v203 offset:13344
	s_waitcnt lgkmcnt(2)
	v_mfma_f32_32x32x16_bf16 v[48:63], v[80:83], v[64:67], v[48:63]
	v_exp_f32_e32 v225, v88
	v_exp_f32_e32 v224, v72
	v_exp_f32_e32 v88, v73
	v_exp_f32_e32 v89, v89
	v_exp_f32_e32 v227, v90
	v_exp_f32_e32 v91, v91
	v_exp_f32_e32 v229, v92
	v_mfma_f32_32x32x16_bf16 v[16:31], v[80:83], v[68:71], v[16:31]
	ds_read_b128 v[80:83], v203 offset:17952
	v_exp_f32_e32 v93, v93
	v_exp_f32_e32 v231, v94
	v_exp_f32_e32 v95, v95
	v_exp_f32_e32 v226, v74
	v_exp_f32_e32 v90, v75
	v_exp_f32_e32 v228, v76
	s_waitcnt lgkmcnt(2)
	v_mfma_f32_32x32x16_bf16 v[32:47], v[204:207], v[64:67], v[32:47]
	v_exp_f32_e32 v92, v77
	v_add_f32_e32 v64, v210, v208
	v_add_f32_e32 v65, v211, v209
	v_exp_f32_e32 v230, v78
	v_add_f32_e32 v208, v212, v64
	v_add_f32_e32 v209, v213, v65
	v_exp_f32_e32 v94, v79
	v_add_f32_e32 v72, v214, v208
	v_add_f32_e32 v73, v215, v209
	v_mfma_f32_32x32x16_bf16 v[0:15], v[204:207], v[68:71], v[0:15]
	v_add_f32_e64 v72, v216, v72
	v_add_f32_e64 v73, v217, v73
	v_cvt_pk_bf16_f32 v64, v225, v89
	v_add_f32_e64 v72, v218, v72
	v_add_f32_e64 v73, v219, v73
	v_cvt_pk_bf16_f32 v65, v227, v91
	v_add_f32_e32 v72, v220, v72
	v_add_f32_e32 v73, v221, v73
	v_cvt_pk_bf16_f32 v66, v229, v93
	v_add_f32_e32 v72, v222, v72
	v_add_f32_e32 v73, v223, v73
	v_cvt_pk_bf16_f32 v67, v231, v95
	v_cvt_pk_bf16_f32 v68, v224, v88
	v_cvt_pk_bf16_f32 v69, v226, v90
	v_cvt_pk_bf16_f32 v70, v228, v92
	v_cvt_pk_bf16_f32 v71, v230, v94
	v_add_f32_e32 v72, v224, v72
	v_add_f32_e32 v73, v225, v73
	s_waitcnt lgkmcnt(1)
	v_mfma_f32_32x32x16_bf16 v[48:63], v[84:87], v[64:67], v[48:63]
	v_add_f32_e64 v72, v88, v72
	v_add_f32_e64 v73, v89, v73
	s_cmp_lg_u32 s68, 0
	s_mov_b32 s68, 1
	v_mfma_f32_32x32x16_bf16 v[16:31], v[84:87], v[68:71], v[16:31]
	s_waitcnt lgkmcnt(0)
	v_mfma_f32_32x32x16_bf16 v[32:47], v[80:83], v[64:67], v[32:47]
	v_add_f32_e64 v64, v226, v72
	v_add_f32_e64 v65, v227, v73
	v_add_f32_e64 v64, v90, v64
	v_add_f32_e64 v65, v91, v65
	v_add_f32_e64 v64, v228, v64
	v_add_f32_e64 v65, v229, v65
	v_add_f32_e32 v64, v92, v64
	v_add_f32_e32 v65, v93, v65
	v_mfma_f32_32x32x16_bf16 v[0:15], v[80:83], v[68:71], v[0:15]
	v_add_f32_e64 v64, v230, v64
	v_add_f32_e64 v65, v231, v65
	v_add_f32_e64 v64, v94, v64
	v_add_f32_e64 v65, v95, v65
	v_add_f32_e64 v150, v150, v64
	v_add_f32_e64 v151, v151, v65
	s_cbranch_scc1 .LBB0_889
	s_mov_b64 s[64:65], 0
	s_and_b64 vcc, exec, s[62:63]
	v_lshl_or_b32 v203, s68, 5, v190
	s_cbranch_vccz .LBB0_882
.LBB0_883:
	v_mad_u32_u24 v203, v203, s82, v201
	ds_read_b128 v[204:207], v203
	ds_read_b128 v[208:211], v203 offset:32
	s_nop 5
	v_xor_b32_e32 v80, 0x80000000, v199
	v_xor_b32_e32 v64, 0x80000000, v200
	v_mov_b32_e32 v81, v80
	v_mov_b32_e32 v82, v80
	v_mov_b32_e32 v83, v80
	v_mov_b32_e32 v84, v80
	v_mov_b32_e32 v85, v80
	v_mov_b32_e32 v86, v80
	v_mov_b32_e32 v87, v80
	v_mov_b32_e32 v88, v80
	v_mov_b32_e32 v89, v80
	v_mov_b32_e32 v90, v80
	v_mov_b32_e32 v91, v80
	v_mov_b32_e32 v92, v80
	v_mov_b32_e32 v93, v80
	v_mov_b32_e32 v94, v80
	v_mov_b32_e32 v95, v80
	v_mov_b32_e32 v65, v64
	v_mov_b32_e32 v66, v64
	v_mov_b32_e32 v67, v64
	v_mov_b32_e32 v68, v64
	v_mov_b32_e32 v69, v64
	v_mov_b32_e32 v70, v64
	v_mov_b32_e32 v71, v64
	v_mov_b32_e32 v72, v64
	v_mov_b32_e32 v73, v64
	v_mov_b32_e32 v74, v64
	v_mov_b32_e32 v75, v64
	v_mov_b32_e32 v76, v64
	v_mov_b32_e32 v77, v64
	v_mov_b32_e32 v78, v64
	v_mov_b32_e32 v79, v64
	s_waitcnt lgkmcnt(0)
	v_mfma_f32_32x32x16_bf16 v[80:95], v[204:207], v[96:99], v[80:95]
	v_mfma_f32_32x32x16_bf16 v[64:79], v[204:207], v[136:139], v[64:79]
	v_mfma_f32_32x32x16_bf16 v[80:95], v[208:211], v[100:103], v[80:95]
	v_mfma_f32_32x32x16_bf16 v[64:79], v[208:211], v[120:123], v[64:79]
	ds_read_b128 v[204:207], v203 offset:64
	ds_read_b128 v[208:211], v203 offset:96
	s_waitcnt lgkmcnt(0)
	v_mfma_f32_32x32x16_bf16 v[80:95], v[204:207], v[104:107], v[80:95]
	v_mfma_f32_32x32x16_bf16 v[64:79], v[204:207], v[124:127], v[64:79]
	v_mfma_f32_32x32x16_bf16 v[80:95], v[208:211], v[108:111], v[80:95]
	v_mfma_f32_32x32x16_bf16 v[64:79], v[208:211], v[128:131], v[64:79]
	ds_read_b128 v[204:207], v203 offset:128
	ds_read_b128 v[208:211], v203 offset:160
	s_waitcnt lgkmcnt(0)
	v_mfma_f32_32x32x16_bf16 v[80:95], v[204:207], v[112:115], v[80:95]
	v_mfma_f32_32x32x16_bf16 v[64:79], v[204:207], v[132:135], v[64:79]
	v_mfma_f32_32x32x16_bf16 v[80:95], v[208:211], v[116:119], v[80:95]
	v_mfma_f32_32x32x16_bf16 v[64:79], v[208:211], v[140:143], v[64:79]
	s_branch .LBB0_885

.Lhwat1_tail:
.LBB0_2115:
	s_bitcmp1_b32 s88, 0
	s_cselect_b32 s30, 0x5800, 0
	v_or_b32_e32 v201, s30, v144
	s_mov_b32 s68, 0
	v_add_u32_e32 v202, v201, v198
	s_and_b64 vcc, exec, s[62:63]
	v_lshl_or_b32 v203, s68, 5, v190
	s_cbranch_vccnz .LBB0_2117
.LBB0_2116:
	v_mad_u32_u24 v212, v203, s81, v201
	ds_read_b128 v[64:67], v212
	ds_read_b128 v[204:207], v212 offset:32
	ds_read_b128 v[208:211], v212 offset:64
	ds_read_b128 v[246:249], v212 offset:96
	s_waitcnt lgkmcnt(2)
	v_mfma_f32_32x32x16_bf16 v[80:95], v[64:67], v[96:99], 0
	v_mfma_f32_32x32x16_bf16 v[64:79], v[64:67], v[136:139], 0
	v_mfma_f32_32x32x16_bf16 v[80:95], v[204:207], v[100:103], v[80:95]
	v_mfma_f32_32x32x16_bf16 v[64:79], v[204:207], v[120:123], v[64:79]
	ds_read_b128 v[204:207], v212 offset:128
	ds_read_b128 v[250:253], v212 offset:160
	s_waitcnt lgkmcnt(2)
	v_mfma_f32_32x32x16_bf16 v[80:95], v[208:211], v[104:107], v[80:95]
	v_mfma_f32_32x32x16_bf16 v[64:79], v[208:211], v[124:127], v[64:79]
	v_mfma_f32_32x32x16_bf16 v[80:95], v[246:249], v[108:111], v[80:95]
	v_mfma_f32_32x32x16_bf16 v[64:79], v[246:249], v[128:131], v[64:79]
	s_waitcnt lgkmcnt(0)
	v_mfma_f32_32x32x16_bf16 v[80:95], v[204:207], v[112:115], v[80:95]
	v_mfma_f32_32x32x16_bf16 v[64:79], v[204:207], v[132:135], v[64:79]
	v_mfma_f32_32x32x16_bf16 v[80:95], v[250:253], v[116:119], v[80:95]
	v_mfma_f32_32x32x16_bf16 v[64:79], v[250:253], v[140:143], v[64:79]

.LBB0_2117:
	v_mad_u32_u24 v203, v203, s81, v201
	ds_read_b128 v[204:207], v203
	ds_read_b128 v[208:211], v203 offset:32
	s_nop 5
	v_xor_b32_e32 v80, 0x80000000, v199
	v_xor_b32_e32 v64, 0x80000000, v200
	v_mov_b32_e32 v81, v80
	v_mov_b32_e32 v82, v80
	v_mov_b32_e32 v83, v80
	v_mov_b32_e32 v84, v80
	v_mov_b32_e32 v85, v80
	v_mov_b32_e32 v86, v80
	v_mov_b32_e32 v87, v80
	v_mov_b32_e32 v88, v80
	v_mov_b32_e32 v89, v80
	v_mov_b32_e32 v90, v80
	v_mov_b32_e32 v91, v80
	v_mov_b32_e32 v92, v80
	v_mov_b32_e32 v93, v80
	v_mov_b32_e32 v94, v80
	v_mov_b32_e32 v95, v80
	v_mov_b32_e32 v65, v64
	v_mov_b32_e32 v66, v64
	v_mov_b32_e32 v67, v64
	v_mov_b32_e32 v68, v64
	v_mov_b32_e32 v69, v64
	v_mov_b32_e32 v70, v64
	v_mov_b32_e32 v71, v64
	v_mov_b32_e32 v72, v64
	v_mov_b32_e32 v73, v64
	v_mov_b32_e32 v74, v64
	v_mov_b32_e32 v75, v64
	v_mov_b32_e32 v76, v64
	v_mov_b32_e32 v77, v64
	v_mov_b32_e32 v78, v64
	v_mov_b32_e32 v79, v64
	s_waitcnt lgkmcnt(0)
	v_mfma_f32_32x32x16_bf16 v[80:95], v[204:207], v[96:99], v[80:95]
	v_mfma_f32_32x32x16_bf16 v[64:79], v[204:207], v[136:139], v[64:79]
	v_mfma_f32_32x32x16_bf16 v[80:95], v[208:211], v[100:103], v[80:95]
	v_mfma_f32_32x32x16_bf16 v[64:79], v[208:211], v[120:123], v[64:79]
	ds_read_b128 v[204:207], v203 offset:64
	ds_read_b128 v[208:211], v203 offset:96
	s_waitcnt lgkmcnt(0)
	v_mfma_f32_32x32x16_bf16 v[80:95], v[204:207], v[104:107], v[80:95]
	v_mfma_f32_32x32x16_bf16 v[64:79], v[204:207], v[124:127], v[64:79]
	v_mfma_f32_32x32x16_bf16 v[80:95], v[208:211], v[108:111], v[80:95]
	v_mfma_f32_32x32x16_bf16 v[64:79], v[208:211], v[128:131], v[64:79]
	ds_read_b128 v[204:207], v203 offset:128
	ds_read_b128 v[208:211], v203 offset:160
	s_waitcnt lgkmcnt(0)
	v_mfma_f32_32x32x16_bf16 v[80:95], v[204:207], v[112:115], v[80:95]
	v_mfma_f32_32x32x16_bf16 v[64:79], v[204:207], v[132:135], v[64:79]
	v_mfma_f32_32x32x16_bf16 v[80:95], v[208:211], v[116:119], v[80:95]
	v_mfma_f32_32x32x16_bf16 v[64:79], v[208:211], v[140:143], v[64:79]
	s_branch .LBB0_2119
